# w2 epilogue: final f32 output stores use the default write-back policy instead of nt (baseline st_nt); rest as v183
# speedup vs baseline: 1.0025x; 1.0012x over previous
.Lepi_w2:
	s_lshl_b32 s9, s9, 8
	s_add_i32 s9, s9, s60
	s_lshl_b32 s78, s8, 8
	s_or_b32 s78, s78, s26
	s_mov_b32 s8, s9
	s_mul_i32 s9, s9, 0x1000
	s_mul_i32 s41, s78, 4
	s_add_i32 s9, s9, s41
	s_lshr_b32 s8, s8, 11
	s_mul_i32 s8, s8, 0x6000
	s_lshl_b32 s41, s78, 2
	s_add_i32 s8, s8, s41
	s_add_i32 s8, s8, 0x5000
	s_add_u32 s74, s36, s8
	s_addc_u32 s75, s37, 0
	v_lshlrev_b32_e32 v131, 2, v176
	global_load_dwordx4 v[132:135], v131, s[74:75] offset:0
	global_load_dwordx4 v[152:155], v131, s[74:75] offset:16
	global_load_dwordx4 v[156:159], v131, s[74:75] offset:512
	global_load_dwordx4 v[160:163], v131, s[74:75] offset:528
	s_add_u32 s38, s94, s9
	s_addc_u32 s39, s95, 0
	s_add_u32 s46, s94, s9
	s_addc_u32 s47, s95, 0
	s_add_u32 s68, s36, s9
	s_addc_u32 s69, s37, 0
	s_add_u32 s68, s68, 0x17600000
	s_addc_u32 s69, s69, 0
	s_cmp_lg_u64 s[42:43], 0
	s_cselect_b32 s46, s46, s68
	s_cselect_b32 s47, s47, s69
	v_lshlrev_b32_e32 v130, 12, v1
	v_lshl_add_u32 v130, v176, 2, v130
	global_load_dwordx4 v[164:167], v130, s[38:39] offset:0
	global_load_dwordx4 v[168:171], v130, s[38:39] offset:16
	global_load_dwordx4 v[172:175], v130, s[38:39] offset:512
	global_load_dwordx4 v[180:183], v130, s[38:39] offset:528
	s_add_u32 s38, s38, 0x10000
	s_addc_u32 s39, s39, 0
	global_load_dwordx4 v[184:187], v130, s[38:39] offset:0
	global_load_dwordx4 v[188:191], v130, s[38:39] offset:16
	global_load_dwordx4 v[192:195], v130, s[38:39] offset:512
	global_load_dwordx4 v[196:199], v130, s[38:39] offset:528
	s_add_u32 s38, s38, 0x10000
	s_addc_u32 s39, s39, 0
	global_load_dwordx4 v[200:203], v130, s[38:39] offset:0
	global_load_dwordx4 v[210:213], v130, s[38:39] offset:16
	global_load_dwordx4 v[214:217], v130, s[38:39] offset:512
	global_load_dwordx4 v[228:231], v130, s[38:39] offset:528
	s_add_u32 s38, s38, 0x10000
	s_addc_u32 s39, s39, 0
	global_load_dwordx4 v[232:235], v130, s[38:39] offset:0
	global_load_dwordx4 v[236:239], v130, s[38:39] offset:16
	global_load_dwordx4 v[240:243], v130, s[38:39] offset:512
	global_load_dwordx4 v[244:247], v130, s[38:39] offset:528
	s_waitcnt vmcnt(14)
	v_pk_fma_f32 v[164:165], v[126:127], v[132:133], v[164:165]
	v_pk_fma_f32 v[166:167], v[128:129], v[134:135], v[166:167]
	v_pk_fma_f32 v[168:169], v[122:123], v[152:153], v[168:169]
	v_pk_fma_f32 v[170:171], v[124:125], v[154:155], v[170:171]
	global_store_dwordx4 v130, v[164:167], s[46:47] offset:0
	global_store_dwordx4 v130, v[168:171], s[46:47] offset:16
	s_nop 0
	s_add_u32 s38, s38, 0x50000
	s_addc_u32 s39, s39, 0
	global_load_dwordx4 v[164:167], v130, s[38:39] offset:0
	global_load_dwordx4 v[168:171], v130, s[38:39] offset:16
	s_waitcnt vmcnt(16)
	v_pk_fma_f32 v[172:173], v[118:119], v[156:157], v[172:173]
	v_pk_fma_f32 v[174:175], v[120:121], v[158:159], v[174:175]
	v_pk_fma_f32 v[180:181], v[114:115], v[160:161], v[180:181]
	v_pk_fma_f32 v[182:183], v[116:117], v[162:163], v[182:183]
	global_store_dwordx4 v130, v[172:175], s[46:47] offset:512
	global_store_dwordx4 v130, v[180:183], s[46:47] offset:528
	s_nop 0
	global_load_dwordx4 v[172:175], v130, s[38:39] offset:512
	global_load_dwordx4 v[180:183], v130, s[38:39] offset:528
	s_waitcnt vmcnt(18)
	v_pk_fma_f32 v[184:185], v[110:111], v[132:133], v[184:185]
	v_pk_fma_f32 v[186:187], v[112:113], v[134:135], v[186:187]
	v_pk_fma_f32 v[188:189], v[106:107], v[152:153], v[188:189]
	v_pk_fma_f32 v[190:191], v[108:109], v[154:155], v[190:191]
	s_add_u32 s46, s46, 0x10000
	s_addc_u32 s47, s47, 0
	global_store_dwordx4 v130, v[184:187], s[46:47] offset:0
	global_store_dwordx4 v130, v[188:191], s[46:47] offset:16
	s_nop 0
	s_add_u32 s38, s38, 0x10000
	s_addc_u32 s39, s39, 0
	global_load_dwordx4 v[184:187], v130, s[38:39] offset:0
	global_load_dwordx4 v[188:191], v130, s[38:39] offset:16
	s_waitcnt vmcnt(20)
	v_pk_fma_f32 v[192:193], v[102:103], v[156:157], v[192:193]
	v_pk_fma_f32 v[194:195], v[104:105], v[158:159], v[194:195]
	v_pk_fma_f32 v[196:197], v[98:99], v[160:161], v[196:197]
	v_pk_fma_f32 v[198:199], v[100:101], v[162:163], v[198:199]
	global_store_dwordx4 v130, v[192:195], s[46:47] offset:512
	global_store_dwordx4 v130, v[196:199], s[46:47] offset:528
	s_nop 0
	global_load_dwordx4 v[192:195], v130, s[38:39] offset:512
	global_load_dwordx4 v[196:199], v130, s[38:39] offset:528
	s_waitcnt vmcnt(22)
	v_pk_fma_f32 v[200:201], v[94:95], v[132:133], v[200:201]
	v_pk_fma_f32 v[202:203], v[96:97], v[134:135], v[202:203]
	v_pk_fma_f32 v[210:211], v[90:91], v[152:153], v[210:211]
	v_pk_fma_f32 v[212:213], v[92:93], v[154:155], v[212:213]
	s_add_u32 s46, s46, 0x10000
	s_addc_u32 s47, s47, 0
	global_store_dwordx4 v130, v[200:203], s[46:47] offset:0
	global_store_dwordx4 v130, v[210:213], s[46:47] offset:16
	s_nop 0
	s_add_u32 s38, s38, 0x10000
	s_addc_u32 s39, s39, 0
	global_load_dwordx4 v[200:203], v130, s[38:39] offset:0
	global_load_dwordx4 v[210:213], v130, s[38:39] offset:16
	s_waitcnt vmcnt(24)
	v_pk_fma_f32 v[214:215], v[86:87], v[156:157], v[214:215]
	v_pk_fma_f32 v[216:217], v[88:89], v[158:159], v[216:217]
	v_pk_fma_f32 v[228:229], v[82:83], v[160:161], v[228:229]
	v_pk_fma_f32 v[230:231], v[84:85], v[162:163], v[230:231]
	global_store_dwordx4 v130, v[214:217], s[46:47] offset:512
	global_store_dwordx4 v130, v[228:231], s[46:47] offset:528
	s_nop 0
	global_load_dwordx4 v[214:217], v130, s[38:39] offset:512
	global_load_dwordx4 v[228:231], v130, s[38:39] offset:528
	s_waitcnt vmcnt(26)
	v_pk_fma_f32 v[232:233], v[78:79], v[132:133], v[232:233]
	v_pk_fma_f32 v[234:235], v[80:81], v[134:135], v[234:235]
	v_pk_fma_f32 v[236:237], v[74:75], v[152:153], v[236:237]
	v_pk_fma_f32 v[238:239], v[76:77], v[154:155], v[238:239]
	s_add_u32 s46, s46, 0x10000
	s_addc_u32 s47, s47, 0
	global_store_dwordx4 v130, v[232:235], s[46:47] offset:0
	global_store_dwordx4 v130, v[236:239], s[46:47] offset:16
	s_nop 0
	s_add_u32 s38, s38, 0x10000
	s_addc_u32 s39, s39, 0
	global_load_dwordx4 v[232:235], v130, s[38:39] offset:0
	global_load_dwordx4 v[236:239], v130, s[38:39] offset:16
	s_waitcnt vmcnt(28)
	v_pk_fma_f32 v[240:241], v[70:71], v[156:157], v[240:241]
	v_pk_fma_f32 v[242:243], v[72:73], v[158:159], v[242:243]
	v_pk_fma_f32 v[244:245], v[66:67], v[160:161], v[244:245]
	v_pk_fma_f32 v[246:247], v[68:69], v[162:163], v[246:247]
	global_store_dwordx4 v130, v[240:243], s[46:47] offset:512
	global_store_dwordx4 v130, v[244:247], s[46:47] offset:528
	s_nop 0
	global_load_dwordx4 v[240:243], v130, s[38:39] offset:512
	global_load_dwordx4 v[244:247], v130, s[38:39] offset:528
	s_waitcnt vmcnt(28)
	v_pk_fma_f32 v[164:165], v[62:63], v[132:133], v[164:165]
	v_pk_fma_f32 v[166:167], v[64:65], v[134:135], v[166:167]
	v_pk_fma_f32 v[168:169], v[58:59], v[152:153], v[168:169]
	v_pk_fma_f32 v[170:171], v[60:61], v[154:155], v[170:171]
	s_add_u32 s46, s46, 0x50000
	s_addc_u32 s47, s47, 0
	global_store_dwordx4 v130, v[164:167], s[46:47] offset:0
	global_store_dwordx4 v130, v[168:171], s[46:47] offset:16
	s_waitcnt vmcnt(26)
	v_pk_fma_f32 v[172:173], v[54:55], v[156:157], v[172:173]
	v_pk_fma_f32 v[174:175], v[56:57], v[158:159], v[174:175]
	v_pk_fma_f32 v[180:181], v[50:51], v[160:161], v[180:181]
	v_pk_fma_f32 v[182:183], v[52:53], v[162:163], v[182:183]
	global_store_dwordx4 v130, v[172:175], s[46:47] offset:512
	global_store_dwordx4 v130, v[180:183], s[46:47] offset:528
	s_waitcnt vmcnt(24)
	v_pk_fma_f32 v[184:185], v[46:47], v[132:133], v[184:185]
	v_pk_fma_f32 v[186:187], v[48:49], v[134:135], v[186:187]
	v_pk_fma_f32 v[188:189], v[42:43], v[152:153], v[188:189]
	v_pk_fma_f32 v[190:191], v[44:45], v[154:155], v[190:191]
	s_add_u32 s46, s46, 0x10000
	s_addc_u32 s47, s47, 0
	global_store_dwordx4 v130, v[184:187], s[46:47] offset:0
	global_store_dwordx4 v130, v[188:191], s[46:47] offset:16
	s_waitcnt vmcnt(22)
	v_pk_fma_f32 v[192:193], v[38:39], v[156:157], v[192:193]
	v_pk_fma_f32 v[194:195], v[40:41], v[158:159], v[194:195]
	v_pk_fma_f32 v[196:197], v[34:35], v[160:161], v[196:197]
	v_pk_fma_f32 v[198:199], v[36:37], v[162:163], v[198:199]
	global_store_dwordx4 v130, v[192:195], s[46:47] offset:512
	global_store_dwordx4 v130, v[196:199], s[46:47] offset:528
	s_waitcnt vmcnt(20)
	v_pk_fma_f32 v[200:201], v[30:31], v[132:133], v[200:201]
	v_pk_fma_f32 v[202:203], v[32:33], v[134:135], v[202:203]
	v_pk_fma_f32 v[210:211], v[26:27], v[152:153], v[210:211]
	v_pk_fma_f32 v[212:213], v[28:29], v[154:155], v[212:213]
	s_add_u32 s46, s46, 0x10000
	s_addc_u32 s47, s47, 0
	global_store_dwordx4 v130, v[200:203], s[46:47] offset:0
	global_store_dwordx4 v130, v[210:213], s[46:47] offset:16
	s_waitcnt vmcnt(18)
	v_pk_fma_f32 v[214:215], v[22:23], v[156:157], v[214:215]
	v_pk_fma_f32 v[216:217], v[24:25], v[158:159], v[216:217]
	v_pk_fma_f32 v[228:229], v[18:19], v[160:161], v[228:229]
	v_pk_fma_f32 v[230:231], v[20:21], v[162:163], v[230:231]
	global_store_dwordx4 v130, v[214:217], s[46:47] offset:512
	global_store_dwordx4 v130, v[228:231], s[46:47] offset:528
	s_waitcnt vmcnt(16)
	v_pk_fma_f32 v[232:233], v[14:15], v[132:133], v[232:233]
	v_pk_fma_f32 v[234:235], v[16:17], v[134:135], v[234:235]
	v_pk_fma_f32 v[236:237], v[10:11], v[152:153], v[236:237]
	v_pk_fma_f32 v[238:239], v[12:13], v[154:155], v[238:239]
	s_add_u32 s46, s46, 0x10000
	s_addc_u32 s47, s47, 0
	global_store_dwordx4 v130, v[232:235], s[46:47] offset:0
	global_store_dwordx4 v130, v[236:239], s[46:47] offset:16
	s_waitcnt vmcnt(14)
	v_pk_fma_f32 v[240:241], v[6:7], v[156:157], v[240:241]
	v_pk_fma_f32 v[242:243], v[8:9], v[158:159], v[242:243]
	v_pk_fma_f32 v[244:245], v[2:3], v[160:161], v[244:245]
	v_pk_fma_f32 v[246:247], v[4:5], v[162:163], v[246:247]
	global_store_dwordx4 v130, v[240:243], s[46:47] offset:512
	global_store_dwordx4 v130, v[244:247], s[46:47] offset:528
	s_branch .LBB0_1251
